# P8 epilogue: skewed software pipeline over the 32 output pairs so transcendental and plain VALU instructions alternate finely (same arithmetic)
# baseline (speedup 1.0000x reference)
; __device__ __forceinline__ u32x4 pack8(f32x4 v0, f32x4 v1) { u32x4 w; w.x = cvt_pk_bf16(v0[0], v0[1]); w.y = cvt_pk_bf16(v0[2], v0[3]); w.z = cvt_pk_bf16(v1[0], v1[1]); w.w = cvt_pk_bf16(v1[2], v1[3]); return w; }
;     __device__ __forceinline__ void operator()(Acc& acc, const Unit& u, int wr, int wc, int fr, int fq, PG8_LAS unsigned char* xl) const {
;     ...
;         for (int ai = 0; ai < 2; ++ai)
; #pragma unroll
;             for (int m = 0; m < 4; ++m) { const int rl = ai * HALF + wr * 64 + m * 16 + fr; const int row = u.r0 + rl; const float s = S[rl], cs = -LOG2E * s, s2 = s * s;
;                 f32x4 o[2];
; #pragma unroll
;                 for (int n = 0; n < 2; ++n) { const f32x4 g = acc[ai][0][m][n], gu = acc[ai][0][m][n] * acc[ai][1][m][n]; f32x4 r;
; #pragma unroll
;                     for (int e = 0; e < 4; ++e) r[e] = gu[e] * (s2 * __builtin_amdgcn_rcpf(1.f + __builtin_amdgcn_exp2f(cs * g[e])));
;                     o[n] = r; }
;                 *(u32x4*)(H + (size_t)row * ldc + (u.c0 >> 1) + wc * 32 + 8 * fq) = pack8(o[0], o[1]); }
.Lrs8_skip:
	ds_read_b32 v184, v148
	ds_read_b32 v185, v150
	ds_read_b32 v186, v152
	ds_read_b32 v187, v155
	ds_read_b32 v188, v157
	ds_read_b32 v189, v159
	ds_read_b32 v190, v161
	ds_read_b32 v191, v163
	s_ashr_i32 s2, s33, 1
	s_ashr_i32 s3, s2, 31
	s_lshl_b64 s[2:3], s[2:3], 1
	v_mov_b64_e32 v[170:171], s[12:13]
	v_mov_b32_e32 v180, 1.0
	s_waitcnt lgkmcnt(0)
	v_pk_mul_f32 v[120:121], v[124:125], v[120:121]
	v_mul_f32_e32 v174, 0xbfb8aa3b, v184
	v_mul_f32_e32 v176, v184, v184
	v_pk_mul_f32 v[122:123], v[126:127], v[122:123]
	v_pk_mul_f32 v[124:125], v[124:125], v[174:175] op_sel_hi:[1,0]
	v_pk_mul_f32 v[112:113], v[116:117], v[112:113]
	v_exp_f32_e32 v124, v124
	v_pk_mul_f32 v[126:127], v[126:127], v[174:175] op_sel_hi:[1,0]
	v_exp_f32_e32 v125, v125
	v_pk_mul_f32 v[114:115], v[118:119], v[114:115]
	v_exp_f32_e32 v126, v126
	v_pk_mul_f32 v[116:117], v[116:117], v[174:175] op_sel_hi:[1,0]
	v_exp_f32_e32 v127, v127
	v_pk_add_f32 v[124:125], v[124:125], v[180:181] op_sel_hi:[1,0]
	v_pk_mul_f32 v[104:105], v[108:109], v[104:105]
	v_exp_f32_e32 v116, v116
	v_pk_mul_f32 v[118:119], v[118:119], v[174:175] op_sel_hi:[1,0]
	v_exp_f32_e32 v117, v117
	v_pk_add_f32 v[126:127], v[126:127], v[180:181] op_sel_hi:[1,0]
	v_rcp_f32_e32 v124, v124
	v_rcp_f32_e32 v125, v125
	v_mul_f32_e32 v182, 0xbfb8aa3b, v185
	v_mul_f32_e32 v192, v185, v185
	v_pk_mul_f32 v[106:107], v[110:111], v[106:107]
	v_exp_f32_e32 v118, v118
	v_pk_mul_f32 v[108:109], v[108:109], v[182:183] op_sel_hi:[1,0]
	v_exp_f32_e32 v119, v119
	v_pk_add_f32 v[116:117], v[116:117], v[180:181] op_sel_hi:[1,0]
	v_rcp_f32_e32 v126, v126
	v_pk_mul_f32 v[124:125], v[124:125], v[176:177] op_sel_hi:[1,0]
	v_rcp_f32_e32 v127, v127
	v_pk_mul_f32 v[96:97], v[100:101], v[96:97]
	v_exp_f32_e32 v108, v108
	v_pk_mul_f32 v[110:111], v[110:111], v[182:183] op_sel_hi:[1,0]
	v_exp_f32_e32 v109, v109
	v_pk_add_f32 v[118:119], v[118:119], v[180:181] op_sel_hi:[1,0]
	v_rcp_f32_e32 v116, v116
	v_pk_mul_f32 v[126:127], v[126:127], v[176:177] op_sel_hi:[1,0]
	v_rcp_f32_e32 v117, v117
	v_pk_mul_f32 v[120:121], v[120:121], v[124:125]
	v_pk_mul_f32 v[98:99], v[102:103], v[98:99]
	v_exp_f32_e32 v110, v110
	v_pk_mul_f32 v[100:101], v[100:101], v[182:183] op_sel_hi:[1,0]
	v_exp_f32_e32 v111, v111
	v_pk_add_f32 v[108:109], v[108:109], v[180:181] op_sel_hi:[1,0]
	v_rcp_f32_e32 v118, v118
	v_pk_mul_f32 v[116:117], v[116:117], v[176:177] op_sel_hi:[1,0]
	v_rcp_f32_e32 v119, v119
	v_pk_mul_f32 v[122:123], v[122:123], v[126:127]
	v_pk_mul_f32 v[88:89], v[92:93], v[88:89]
	v_exp_f32_e32 v100, v100
	v_pk_mul_f32 v[102:103], v[102:103], v[182:183] op_sel_hi:[1,0]
	v_exp_f32_e32 v101, v101
	v_pk_add_f32 v[110:111], v[110:111], v[180:181] op_sel_hi:[1,0]
	v_rcp_f32_e32 v108, v108
	v_pk_mul_f32 v[118:119], v[118:119], v[176:177] op_sel_hi:[1,0]
	v_rcp_f32_e32 v109, v109
	v_pk_mul_f32 v[112:113], v[112:113], v[116:117]
	v_mul_f32_e32 v174, 0xbfb8aa3b, v186
	v_mul_f32_e32 v176, v186, v186
	v_pk_mul_f32 v[90:91], v[94:95], v[90:91]
	v_exp_f32_e32 v102, v102
	v_pk_mul_f32 v[92:93], v[92:93], v[174:175] op_sel_hi:[1,0]
	v_exp_f32_e32 v103, v103
	v_pk_add_f32 v[100:101], v[100:101], v[180:181] op_sel_hi:[1,0]
	v_rcp_f32_e32 v110, v110
	v_pk_mul_f32 v[108:109], v[108:109], v[192:193] op_sel_hi:[1,0]
	v_rcp_f32_e32 v111, v111
	v_pk_mul_f32 v[114:115], v[114:115], v[118:119]
	v_add_u32_e32 v172, s60, v146
	v_mad_i64_i32 v[172:173], s[30:31], v172, s64, v[170:171]
	v_lshl_add_u64 v[172:173], v[172:173], 0, s[2:3]
	v_lshl_add_u64 v[172:173], v[172:173], 0, s[8:9]
	v_lshl_add_u64 v[172:173], v[172:173], 0, v[136:137]
	v_cvt_pk_bf16_f32 v124, v120, v121
	v_cvt_pk_bf16_f32 v125, v122, v123
	v_cvt_pk_bf16_f32 v126, v112, v113
	v_cvt_pk_bf16_f32 v127, v114, v115
	flat_store_dwordx4 v[172:173], v[124:127]
	v_pk_mul_f32 v[80:81], v[84:85], v[80:81]
	v_exp_f32_e32 v92, v92
	v_pk_mul_f32 v[94:95], v[94:95], v[174:175] op_sel_hi:[1,0]
	v_exp_f32_e32 v93, v93
	v_pk_add_f32 v[102:103], v[102:103], v[180:181] op_sel_hi:[1,0]
	v_rcp_f32_e32 v100, v100
	v_pk_mul_f32 v[110:111], v[110:111], v[192:193] op_sel_hi:[1,0]
	v_rcp_f32_e32 v101, v101
	v_pk_mul_f32 v[104:105], v[104:105], v[108:109]
	v_pk_mul_f32 v[82:83], v[86:87], v[82:83]
	v_exp_f32_e32 v94, v94
	v_pk_mul_f32 v[84:85], v[84:85], v[174:175] op_sel_hi:[1,0]
	v_exp_f32_e32 v95, v95
	v_pk_add_f32 v[92:93], v[92:93], v[180:181] op_sel_hi:[1,0]
	v_rcp_f32_e32 v102, v102
	v_pk_mul_f32 v[100:101], v[100:101], v[192:193] op_sel_hi:[1,0]
	v_rcp_f32_e32 v103, v103
	v_pk_mul_f32 v[106:107], v[106:107], v[110:111]
	v_pk_mul_f32 v[72:73], v[76:77], v[72:73]
	v_exp_f32_e32 v84, v84
	v_pk_mul_f32 v[86:87], v[86:87], v[174:175] op_sel_hi:[1,0]
	v_exp_f32_e32 v85, v85
	v_pk_add_f32 v[94:95], v[94:95], v[180:181] op_sel_hi:[1,0]
	v_rcp_f32_e32 v92, v92
	v_pk_mul_f32 v[102:103], v[102:103], v[192:193] op_sel_hi:[1,0]
	v_rcp_f32_e32 v93, v93
	v_pk_mul_f32 v[96:97], v[96:97], v[100:101]
	v_mul_f32_e32 v182, 0xbfb8aa3b, v187
	v_mul_f32_e32 v192, v187, v187
	v_pk_mul_f32 v[74:75], v[78:79], v[74:75]
	v_exp_f32_e32 v86, v86
	v_pk_mul_f32 v[76:77], v[76:77], v[182:183] op_sel_hi:[1,0]
	v_exp_f32_e32 v87, v87
	v_pk_add_f32 v[84:85], v[84:85], v[180:181] op_sel_hi:[1,0]
	v_rcp_f32_e32 v94, v94
	v_pk_mul_f32 v[92:93], v[92:93], v[176:177] op_sel_hi:[1,0]
	v_rcp_f32_e32 v95, v95
	v_pk_mul_f32 v[98:99], v[98:99], v[102:103]
	v_add_co_u32_e32 v172, vcc, 0x16000, v172
	s_nop 1
	v_addc_co_u32_e32 v173, vcc, 0, v173, vcc
	v_cvt_pk_bf16_f32 v108, v104, v105
	v_cvt_pk_bf16_f32 v109, v106, v107
	v_cvt_pk_bf16_f32 v110, v96, v97
	v_cvt_pk_bf16_f32 v111, v98, v99
	flat_store_dwordx4 v[172:173], v[108:111]
	v_pk_mul_f32 v[64:65], v[68:69], v[64:65]
; __device__ __forceinline__ u32x4 pack8(f32x4 v0, f32x4 v1) { u32x4 w; w.x = cvt_pk_bf16(v0[0], v0[1]); w.y = cvt_pk_bf16(v0[2], v0[3]); w.z = cvt_pk_bf16(v1[0], v1[1]); w.w = cvt_pk_bf16(v1[2], v1[3]); return w; }
;     __device__ __forceinline__ void operator()(Acc& acc, const Unit& u, int wr, int wc, int fr, int fq, PG8_LAS unsigned char* xl) const {
;     ...
;         for (int ai = 0; ai < 2; ++ai)
; #pragma unroll
;             for (int m = 0; m < 4; ++m) { const int rl = ai * HALF + wr * 64 + m * 16 + fr; const int row = u.r0 + rl; const float s = S[rl], cs = -LOG2E * s, s2 = s * s;
;                 f32x4 o[2];
; #pragma unroll
;                 for (int n = 0; n < 2; ++n) { const f32x4 g = acc[ai][0][m][n], gu = acc[ai][0][m][n] * acc[ai][1][m][n]; f32x4 r;
; #pragma unroll
;                     for (int e = 0; e < 4; ++e) r[e] = gu[e] * (s2 * __builtin_amdgcn_rcpf(1.f + __builtin_amdgcn_exp2f(cs * g[e])));
;                     o[n] = r; }
;                 *(u32x4*)(H + (size_t)row * ldc + (u.c0 >> 1) + wc * 32 + 8 * fq) = pack8(o[0], o[1]); }
	v_exp_f32_e32 v76, v76
	v_pk_mul_f32 v[78:79], v[78:79], v[182:183] op_sel_hi:[1,0]
	v_exp_f32_e32 v77, v77
	v_pk_add_f32 v[86:87], v[86:87], v[180:181] op_sel_hi:[1,0]
	v_rcp_f32_e32 v84, v84
	v_pk_mul_f32 v[94:95], v[94:95], v[176:177] op_sel_hi:[1,0]
	v_rcp_f32_e32 v85, v85
	v_pk_mul_f32 v[88:89], v[88:89], v[92:93]
	v_pk_mul_f32 v[66:67], v[70:71], v[66:67]
	v_exp_f32_e32 v78, v78
	v_pk_mul_f32 v[68:69], v[68:69], v[182:183] op_sel_hi:[1,0]
	v_exp_f32_e32 v79, v79
	v_pk_add_f32 v[76:77], v[76:77], v[180:181] op_sel_hi:[1,0]
	v_rcp_f32_e32 v86, v86
	v_pk_mul_f32 v[84:85], v[84:85], v[176:177] op_sel_hi:[1,0]
	v_rcp_f32_e32 v87, v87
	v_pk_mul_f32 v[90:91], v[90:91], v[94:95]
	v_pk_mul_f32 v[56:57], v[60:61], v[56:57]
	v_exp_f32_e32 v68, v68
	v_pk_mul_f32 v[70:71], v[70:71], v[182:183] op_sel_hi:[1,0]
	v_exp_f32_e32 v69, v69
	v_pk_add_f32 v[78:79], v[78:79], v[180:181] op_sel_hi:[1,0]
	v_rcp_f32_e32 v76, v76
	v_pk_mul_f32 v[86:87], v[86:87], v[176:177] op_sel_hi:[1,0]
	v_rcp_f32_e32 v77, v77
	v_pk_mul_f32 v[80:81], v[80:81], v[84:85]
	v_mul_f32_e32 v174, 0xbfb8aa3b, v188
	v_mul_f32_e32 v176, v188, v188
	v_pk_mul_f32 v[58:59], v[62:63], v[58:59]
	v_exp_f32_e32 v70, v70
	v_pk_mul_f32 v[60:61], v[60:61], v[174:175] op_sel_hi:[1,0]
	v_exp_f32_e32 v71, v71
	v_pk_add_f32 v[68:69], v[68:69], v[180:181] op_sel_hi:[1,0]
	v_rcp_f32_e32 v78, v78
	v_pk_mul_f32 v[76:77], v[76:77], v[192:193] op_sel_hi:[1,0]
	v_rcp_f32_e32 v79, v79
	v_pk_mul_f32 v[82:83], v[82:83], v[86:87]
	v_add_co_u32_e32 v172, vcc, 0x16000, v172
	s_nop 1
	v_addc_co_u32_e32 v173, vcc, 0, v173, vcc
	v_cvt_pk_bf16_f32 v92, v88, v89
	v_cvt_pk_bf16_f32 v93, v90, v91
	v_cvt_pk_bf16_f32 v94, v80, v81
	v_cvt_pk_bf16_f32 v95, v82, v83
	flat_store_dwordx4 v[172:173], v[92:95]
	v_pk_mul_f32 v[48:49], v[52:53], v[48:49]
	v_exp_f32_e32 v60, v60
	v_pk_mul_f32 v[62:63], v[62:63], v[174:175] op_sel_hi:[1,0]
	v_exp_f32_e32 v61, v61
	v_pk_add_f32 v[70:71], v[70:71], v[180:181] op_sel_hi:[1,0]
	v_rcp_f32_e32 v68, v68
	v_pk_mul_f32 v[78:79], v[78:79], v[192:193] op_sel_hi:[1,0]
	v_rcp_f32_e32 v69, v69
	v_pk_mul_f32 v[72:73], v[72:73], v[76:77]
	v_pk_mul_f32 v[50:51], v[54:55], v[50:51]
	v_exp_f32_e32 v62, v62
	v_pk_mul_f32 v[52:53], v[52:53], v[174:175] op_sel_hi:[1,0]
	v_exp_f32_e32 v63, v63
	v_pk_add_f32 v[60:61], v[60:61], v[180:181] op_sel_hi:[1,0]
	v_rcp_f32_e32 v70, v70
	v_pk_mul_f32 v[68:69], v[68:69], v[192:193] op_sel_hi:[1,0]
	v_rcp_f32_e32 v71, v71
	v_pk_mul_f32 v[74:75], v[74:75], v[78:79]
	v_pk_mul_f32 v[40:41], v[44:45], v[40:41]
	v_exp_f32_e32 v52, v52
	v_pk_mul_f32 v[54:55], v[54:55], v[174:175] op_sel_hi:[1,0]
	v_exp_f32_e32 v53, v53
	v_pk_add_f32 v[62:63], v[62:63], v[180:181] op_sel_hi:[1,0]
	v_rcp_f32_e32 v60, v60
	v_pk_mul_f32 v[70:71], v[70:71], v[192:193] op_sel_hi:[1,0]
	v_rcp_f32_e32 v61, v61
	v_pk_mul_f32 v[64:65], v[64:65], v[68:69]
	v_mul_f32_e32 v182, 0xbfb8aa3b, v189
	v_mul_f32_e32 v192, v189, v189
	v_pk_mul_f32 v[42:43], v[46:47], v[42:43]
	v_exp_f32_e32 v54, v54
	v_pk_mul_f32 v[44:45], v[44:45], v[182:183] op_sel_hi:[1,0]
	v_exp_f32_e32 v55, v55
	v_pk_add_f32 v[52:53], v[52:53], v[180:181] op_sel_hi:[1,0]
	v_rcp_f32_e32 v62, v62
	v_pk_mul_f32 v[60:61], v[60:61], v[176:177] op_sel_hi:[1,0]
	v_rcp_f32_e32 v63, v63
	v_pk_mul_f32 v[66:67], v[66:67], v[70:71]
	v_add_co_u32_e32 v172, vcc, 0x16000, v172
	s_nop 1
	v_addc_co_u32_e32 v173, vcc, 0, v173, vcc
	v_cvt_pk_bf16_f32 v76, v72, v73
	v_cvt_pk_bf16_f32 v77, v74, v75
	v_cvt_pk_bf16_f32 v78, v64, v65
	v_cvt_pk_bf16_f32 v79, v66, v67
	flat_store_dwordx4 v[172:173], v[76:79]
	v_pk_mul_f32 v[32:33], v[36:37], v[32:33]
	v_exp_f32_e32 v44, v44
	v_pk_mul_f32 v[46:47], v[46:47], v[182:183] op_sel_hi:[1,0]
	v_exp_f32_e32 v45, v45
	v_pk_add_f32 v[54:55], v[54:55], v[180:181] op_sel_hi:[1,0]
	v_rcp_f32_e32 v52, v52
	v_pk_mul_f32 v[62:63], v[62:63], v[176:177] op_sel_hi:[1,0]
	v_rcp_f32_e32 v53, v53
	v_pk_mul_f32 v[56:57], v[56:57], v[60:61]
	v_pk_mul_f32 v[34:35], v[38:39], v[34:35]
	v_exp_f32_e32 v46, v46
	v_pk_mul_f32 v[36:37], v[36:37], v[182:183] op_sel_hi:[1,0]
	v_exp_f32_e32 v47, v47
	v_pk_add_f32 v[44:45], v[44:45], v[180:181] op_sel_hi:[1,0]
	v_rcp_f32_e32 v54, v54
	v_pk_mul_f32 v[52:53], v[52:53], v[176:177] op_sel_hi:[1,0]
	v_rcp_f32_e32 v55, v55
	v_pk_mul_f32 v[58:59], v[58:59], v[62:63]
	v_pk_mul_f32 v[24:25], v[28:29], v[24:25]
	v_exp_f32_e32 v36, v36
	v_pk_mul_f32 v[38:39], v[38:39], v[182:183] op_sel_hi:[1,0]
	v_exp_f32_e32 v37, v37
	v_pk_add_f32 v[46:47], v[46:47], v[180:181] op_sel_hi:[1,0]
	v_rcp_f32_e32 v44, v44
	v_pk_mul_f32 v[54:55], v[54:55], v[176:177] op_sel_hi:[1,0]
	v_rcp_f32_e32 v45, v45
	v_pk_mul_f32 v[48:49], v[48:49], v[52:53]
	v_mul_f32_e32 v174, 0xbfb8aa3b, v190
	v_mul_f32_e32 v176, v190, v190
	v_pk_mul_f32 v[26:27], v[30:31], v[26:27]
	v_exp_f32_e32 v38, v38
; __device__ __forceinline__ u32x4 pack8(f32x4 v0, f32x4 v1) { u32x4 w; w.x = cvt_pk_bf16(v0[0], v0[1]); w.y = cvt_pk_bf16(v0[2], v0[3]); w.z = cvt_pk_bf16(v1[0], v1[1]); w.w = cvt_pk_bf16(v1[2], v1[3]); return w; }
;     __device__ __forceinline__ void operator()(Acc& acc, const Unit& u, int wr, int wc, int fr, int fq, PG8_LAS unsigned char* xl) const {
;     ...
;             for (int m = 0; m < 4; ++m) { const int rl = ai * HALF + wr * 64 + m * 16 + fr; const int row = u.r0 + rl; const float s = S[rl], cs = -LOG2E * s, s2 = s * s;
;                 f32x4 o[2];
; #pragma unroll
;                 for (int n = 0; n < 2; ++n) { const f32x4 g = acc[ai][0][m][n], gu = acc[ai][0][m][n] * acc[ai][1][m][n]; f32x4 r;
; #pragma unroll
;                     for (int e = 0; e < 4; ++e) r[e] = gu[e] * (s2 * __builtin_amdgcn_rcpf(1.f + __builtin_amdgcn_exp2f(cs * g[e])));
;                     o[n] = r; }
;                 *(u32x4*)(H + (size_t)row * ldc + (u.c0 >> 1) + wc * 32 + 8 * fq) = pack8(o[0], o[1]); }
	v_pk_mul_f32 v[28:29], v[28:29], v[174:175] op_sel_hi:[1,0]
	v_exp_f32_e32 v39, v39
	v_pk_add_f32 v[36:37], v[36:37], v[180:181] op_sel_hi:[1,0]
	v_rcp_f32_e32 v46, v46
	v_pk_mul_f32 v[44:45], v[44:45], v[192:193] op_sel_hi:[1,0]
	v_rcp_f32_e32 v47, v47
	v_pk_mul_f32 v[50:51], v[50:51], v[54:55]
	v_add_co_u32_e32 v172, vcc, 0x6e000, v172
	s_nop 1
	v_addc_co_u32_e32 v173, vcc, 0, v173, vcc
	v_cvt_pk_bf16_f32 v60, v56, v57
	v_cvt_pk_bf16_f32 v61, v58, v59
	v_cvt_pk_bf16_f32 v62, v48, v49
	v_cvt_pk_bf16_f32 v63, v50, v51
	flat_store_dwordx4 v[172:173], v[60:63]
	v_pk_mul_f32 v[16:17], v[20:21], v[16:17]
	v_exp_f32_e32 v28, v28
	v_pk_mul_f32 v[30:31], v[30:31], v[174:175] op_sel_hi:[1,0]
	v_exp_f32_e32 v29, v29
	v_pk_add_f32 v[38:39], v[38:39], v[180:181] op_sel_hi:[1,0]
	v_rcp_f32_e32 v36, v36
	v_pk_mul_f32 v[46:47], v[46:47], v[192:193] op_sel_hi:[1,0]
	v_rcp_f32_e32 v37, v37
	v_pk_mul_f32 v[40:41], v[40:41], v[44:45]
	v_pk_mul_f32 v[18:19], v[22:23], v[18:19]
	v_exp_f32_e32 v30, v30
	v_pk_mul_f32 v[20:21], v[20:21], v[174:175] op_sel_hi:[1,0]
	v_exp_f32_e32 v31, v31
	v_pk_add_f32 v[28:29], v[28:29], v[180:181] op_sel_hi:[1,0]
	v_rcp_f32_e32 v38, v38
	v_pk_mul_f32 v[36:37], v[36:37], v[192:193] op_sel_hi:[1,0]
	v_rcp_f32_e32 v39, v39
	v_pk_mul_f32 v[42:43], v[42:43], v[46:47]
	v_pk_mul_f32 v[8:9], v[12:13], v[8:9]
	v_exp_f32_e32 v20, v20
	v_pk_mul_f32 v[22:23], v[22:23], v[174:175] op_sel_hi:[1,0]
	v_exp_f32_e32 v21, v21
	v_pk_add_f32 v[30:31], v[30:31], v[180:181] op_sel_hi:[1,0]
	v_rcp_f32_e32 v28, v28
	v_pk_mul_f32 v[38:39], v[38:39], v[192:193] op_sel_hi:[1,0]
	v_rcp_f32_e32 v29, v29
	v_pk_mul_f32 v[32:33], v[32:33], v[36:37]
	v_mul_f32_e32 v182, 0xbfb8aa3b, v191
	v_mul_f32_e32 v192, v191, v191
	v_pk_mul_f32 v[10:11], v[14:15], v[10:11]
	v_exp_f32_e32 v22, v22
	v_pk_mul_f32 v[12:13], v[12:13], v[182:183] op_sel_hi:[1,0]
	v_exp_f32_e32 v23, v23
	v_pk_add_f32 v[20:21], v[20:21], v[180:181] op_sel_hi:[1,0]
	v_rcp_f32_e32 v30, v30
	v_pk_mul_f32 v[28:29], v[28:29], v[176:177] op_sel_hi:[1,0]
	v_rcp_f32_e32 v31, v31
	v_pk_mul_f32 v[34:35], v[34:35], v[38:39]
	v_add_co_u32_e32 v172, vcc, 0x16000, v172
	s_nop 1
	v_addc_co_u32_e32 v173, vcc, 0, v173, vcc
	v_cvt_pk_bf16_f32 v44, v40, v41
	v_cvt_pk_bf16_f32 v45, v42, v43
	v_cvt_pk_bf16_f32 v46, v32, v33
	v_cvt_pk_bf16_f32 v47, v34, v35
	flat_store_dwordx4 v[172:173], v[44:47]
	v_pk_mul_f32 v[0:1], v[4:5], v[0:1]
	v_exp_f32_e32 v12, v12
	v_pk_mul_f32 v[14:15], v[14:15], v[182:183] op_sel_hi:[1,0]
	v_exp_f32_e32 v13, v13
	v_pk_add_f32 v[22:23], v[22:23], v[180:181] op_sel_hi:[1,0]
	v_rcp_f32_e32 v20, v20
	v_pk_mul_f32 v[30:31], v[30:31], v[176:177] op_sel_hi:[1,0]
	v_rcp_f32_e32 v21, v21
	v_pk_mul_f32 v[24:25], v[24:25], v[28:29]
	v_pk_mul_f32 v[2:3], v[6:7], v[2:3]
	v_exp_f32_e32 v14, v14
	v_pk_mul_f32 v[4:5], v[4:5], v[182:183] op_sel_hi:[1,0]
	v_exp_f32_e32 v15, v15
	v_pk_add_f32 v[12:13], v[12:13], v[180:181] op_sel_hi:[1,0]
	v_rcp_f32_e32 v22, v22
	v_pk_mul_f32 v[20:21], v[20:21], v[176:177] op_sel_hi:[1,0]
	v_rcp_f32_e32 v23, v23
	v_pk_mul_f32 v[26:27], v[26:27], v[30:31]
	v_exp_f32_e32 v4, v4
	v_pk_mul_f32 v[6:7], v[6:7], v[182:183] op_sel_hi:[1,0]
	v_exp_f32_e32 v5, v5
	v_pk_add_f32 v[14:15], v[14:15], v[180:181] op_sel_hi:[1,0]
	v_rcp_f32_e32 v12, v12
	v_pk_mul_f32 v[22:23], v[22:23], v[176:177] op_sel_hi:[1,0]
	v_rcp_f32_e32 v13, v13
	v_pk_mul_f32 v[16:17], v[16:17], v[20:21]
	v_exp_f32_e32 v6, v6
	v_exp_f32_e32 v7, v7
	v_pk_add_f32 v[4:5], v[4:5], v[180:181] op_sel_hi:[1,0]
	v_rcp_f32_e32 v14, v14
	v_pk_mul_f32 v[12:13], v[12:13], v[192:193] op_sel_hi:[1,0]
	v_rcp_f32_e32 v15, v15
	v_pk_mul_f32 v[18:19], v[18:19], v[22:23]
	v_add_co_u32_e32 v172, vcc, 0x16000, v172
	s_nop 1
	v_addc_co_u32_e32 v173, vcc, 0, v173, vcc
	v_cvt_pk_bf16_f32 v28, v24, v25
	v_cvt_pk_bf16_f32 v29, v26, v27
	v_cvt_pk_bf16_f32 v30, v16, v17
	v_cvt_pk_bf16_f32 v31, v18, v19
	flat_store_dwordx4 v[172:173], v[28:31]
	v_pk_add_f32 v[6:7], v[6:7], v[180:181] op_sel_hi:[1,0]
	v_rcp_f32_e32 v4, v4
	v_pk_mul_f32 v[14:15], v[14:15], v[192:193] op_sel_hi:[1,0]
	v_rcp_f32_e32 v5, v5
	v_pk_mul_f32 v[8:9], v[8:9], v[12:13]
	v_rcp_f32_e32 v6, v6
	v_pk_mul_f32 v[4:5], v[4:5], v[192:193] op_sel_hi:[1,0]
	v_rcp_f32_e32 v7, v7
	v_pk_mul_f32 v[10:11], v[10:11], v[14:15]
	v_pk_mul_f32 v[6:7], v[6:7], v[192:193] op_sel_hi:[1,0]
	v_pk_mul_f32 v[0:1], v[0:1], v[4:5]
	v_pk_mul_f32 v[2:3], v[2:3], v[6:7]
	v_add_co_u32_e32 v172, vcc, 0x16000, v172
	s_nop 1
	v_addc_co_u32_e32 v173, vcc, 0, v173, vcc
	v_cvt_pk_bf16_f32 v12, v8, v9
	v_cvt_pk_bf16_f32 v13, v10, v11
	v_cvt_pk_bf16_f32 v14, v0, v1
	v_cvt_pk_bf16_f32 v15, v2, v3
	flat_store_dwordx4 v[172:173], v[12:15]
	s_andn2_b64 vcc, exec, s[6:7]
	s_mov_b64 s[2:3], -1
	s_cbranch_vccnz .LBB0_821
	s_andn2_b64 vcc, exec, s[10:11]
	s_cbranch_vccnz .LBB0_820
	s_barrier
	s_branch .LBB0_820
